# P3 epilogue: per-chunk counted vmcnt waits for gate and partial-sum loads instead of one full drain
# baseline (speedup 1.0000x reference)
; __device__ __forceinline__ unsigned cvt_pk_bf16(float lo, float hi) { unsigned r; asm volatile("v_cvt_pk_bf16_f32 %0, %1, %2" : "=v"(r) : "v"(lo), "v"(hi)); return r; }
; __device__ __forceinline__ float bf_lo(unsigned w) { return __uint_as_float(w << 16); }
; __device__ __forceinline__ float bf_hi(unsigned w) { return __uint_as_float(w & 0xffff0000u); }
; __device__ __forceinline__ float sigmoidf_(float x) { return __builtin_amdgcn_rcpf(1.0f + __builtin_amdgcn_exp2f(-x * 1.4426950408889634f)); }
;     __device__ __forceinline__ void operator()(const f32x4 (&acc)[2][2][4][2], const Unit& u, int wr, int wc, int fr, int fq) const {
;     ...
;             for (int m = 0; m < 4; ++m) { const int row = row0 + ai * HALF + m * 16;
; #pragma unroll
;                 for (int bj = 0; bj < 2; ++bj) { const int col = col0 + bj * HALF;
;                     const u32x4 g = gv[m][bj];
;                     bf16_t* mp = MIX + (size_t)row * 1024 + col;
;                     f32x4 v0 = acc[ai][bj][m][0], v1 = acc[ai][bj][m][1];
;                     v0[0] *= sigmoidf_(bf_lo(g.x)); v0[1] *= sigmoidf_(bf_hi(g.x)); v0[2] *= sigmoidf_(bf_lo(g.y)); v0[3] *= sigmoidf_(bf_hi(g.y));
;                     v1[0] *= sigmoidf_(bf_lo(g.z)); v1[1] *= sigmoidf_(bf_hi(g.z)); v1[2] *= sigmoidf_(bf_lo(g.w)); v1[3] *= sigmoidf_(bf_hi(g.w));
;                     if (br > 0) { const u32x4 p = pv[m][bj];
;                         v0[0] += bf_lo(p.x); v0[1] += bf_hi(p.x); v0[2] += bf_lo(p.y); v0[3] += bf_hi(p.y); v1[0] += bf_lo(p.z); v1[1] += bf_hi(p.z); v1[2] += bf_lo(p.w); v1[3] += bf_hi(p.w); }
;                     u32x4 w; w.x = cvt_pk_bf16(v0[0], v0[1]); w.y = cvt_pk_bf16(v0[2], v0[3]); w.z = cvt_pk_bf16(v1[0], v1[1]); w.w = cvt_pk_bf16(v1[2], v1[3]);
;                     *(u32x4*)mp = w; } }
.LBB0_417:
	s_waitcnt vmcnt(7)
	v_lshlrev_b32_e32 v192, 16, v188
	v_and_b32_e32 v188, 0xffff0000, v188
	v_mul_f32_e32 v188, 0xbfb8aa3b, v188
	v_exp_f32_e32 v188, v188
	v_mul_f32_e32 v192, 0xbfb8aa3b, v192
	v_exp_f32_e32 v192, v192
	v_add_f32_e32 v188, 1.0, v188
	v_rcp_f32_e32 v249, v188
	v_lshlrev_b32_e32 v188, 16, v189
	v_and_b32_e32 v189, 0xffff0000, v189
	v_mul_f32_e32 v188, 0xbfb8aa3b, v188
	v_mul_f32_e32 v189, 0xbfb8aa3b, v189
	v_exp_f32_e32 v188, v188
	v_exp_f32_e32 v189, v189
	v_add_f32_e32 v192, 1.0, v192
	v_rcp_f32_e32 v248, v192
	v_add_f32_e32 v188, 1.0, v188
	v_add_f32_e32 v189, 1.0, v189
	v_rcp_f32_e32 v188, v188
	v_rcp_f32_e32 v189, v189
	v_pk_mul_f32 v[140:141], v[140:141], v[248:249]
	s_and_b64 vcc, exec, s[6:7]
	v_pk_mul_f32 v[142:143], v[142:143], v[188:189]
	v_lshlrev_b32_e32 v188, 16, v190
	v_and_b32_e32 v189, 0xffff0000, v190
	v_mul_f32_e32 v188, 0xbfb8aa3b, v188
	v_mul_f32_e32 v189, 0xbfb8aa3b, v189
	v_exp_f32_e32 v188, v188
	v_exp_f32_e32 v189, v189
	v_add_f32_e32 v188, 1.0, v188
	v_add_f32_e32 v189, 1.0, v189
	v_rcp_f32_e32 v188, v188
	v_rcp_f32_e32 v189, v189
	s_nop 0
	v_pk_mul_f32 v[188:189], v[128:129], v[188:189]
	v_lshlrev_b32_e32 v128, 16, v191
	v_and_b32_e32 v129, 0xffff0000, v191
	v_mul_f32_e32 v128, 0xbfb8aa3b, v128
	v_mul_f32_e32 v129, 0xbfb8aa3b, v129
	v_exp_f32_e32 v128, v128
	v_exp_f32_e32 v129, v129
	v_add_f32_e32 v128, 1.0, v128
	v_add_f32_e32 v129, 1.0, v129
	v_rcp_f32_e32 v128, v128
	v_rcp_f32_e32 v129, v129
	s_nop 0
	v_pk_mul_f32 v[130:131], v[130:131], v[128:129]
	s_cbranch_vccnz .LBB0_419
	v_lshlrev_b32_e32 v128, 16, v184
	v_and_b32_e32 v129, 0xffff0000, v184
	v_pk_add_f32 v[140:141], v[140:141], v[128:129]
	v_lshlrev_b32_e32 v128, 16, v185
	v_and_b32_e32 v129, 0xffff0000, v185
	v_pk_add_f32 v[142:143], v[142:143], v[128:129]
	v_lshlrev_b32_e32 v128, 16, v186
	v_and_b32_e32 v129, 0xffff0000, v186
	v_pk_add_f32 v[188:189], v[188:189], v[128:129]
	v_lshlrev_b32_e32 v128, 16, v187
	v_and_b32_e32 v129, 0xffff0000, v187
	v_pk_add_f32 v[130:131], v[130:131], v[128:129]
.LBB0_419:
	v_cvt_pk_bf16_f32 v140, v140, v141
	v_cvt_pk_bf16_f32 v141, v142, v143
	v_cvt_pk_bf16_f32 v142, v188, v189
	s_nop 0
	v_cvt_pk_bf16_f32 v143, v130, v131
	s_waitcnt vmcnt(6)
	v_lshlrev_b32_e32 v130, 16, v180
	v_and_b32_e32 v131, 0xffff0000, v180
	v_mul_f32_e32 v130, 0xbfb8aa3b, v130
	v_mul_f32_e32 v131, 0xbfb8aa3b, v131
	v_exp_f32_e32 v130, v130
	v_exp_f32_e32 v131, v131
	v_lshl_add_u64 v[128:129], v[212:213], 1, v[226:227]
	global_store_dwordx4 v[128:129], v[140:143], off
	v_add_f32_e32 v130, 1.0, v130
	v_add_f32_e32 v131, 1.0, v131
	v_lshlrev_b32_e32 v140, 16, v181
	v_and_b32_e32 v141, 0xffff0000, v181
	v_mul_f32_e32 v140, 0xbfb8aa3b, v140
	v_mul_f32_e32 v141, 0xbfb8aa3b, v141
	v_rcp_f32_e32 v130, v130
	v_rcp_f32_e32 v131, v131
	v_exp_f32_e32 v140, v140
	v_exp_f32_e32 v141, v141
	v_lshlrev_b32_e32 v142, 16, v183
	v_pk_mul_f32 v[116:117], v[116:117], v[130:131]
	v_add_f32_e32 v130, 1.0, v140
	v_add_f32_e32 v131, 1.0, v141
	v_lshlrev_b32_e32 v140, 16, v182
	v_and_b32_e32 v141, 0xffff0000, v182
	v_and_b32_e32 v143, 0xffff0000, v183
	v_mul_f32_e32 v140, 0xbfb8aa3b, v140
	v_mul_f32_e32 v141, 0xbfb8aa3b, v141
	v_mul_f32_e32 v142, 0xbfb8aa3b, v142
	v_mul_f32_e32 v143, 0xbfb8aa3b, v143
	v_exp_f32_e32 v140, v140
	v_exp_f32_e32 v141, v141
	v_exp_f32_e32 v142, v142
	v_exp_f32_e32 v143, v143
	v_add_f32_e32 v140, 1.0, v140
	v_add_f32_e32 v141, 1.0, v141
	v_add_f32_e32 v142, 1.0, v142
	v_add_f32_e32 v143, 1.0, v143
	v_rcp_f32_e32 v130, v130
	v_rcp_f32_e32 v131, v131
	v_rcp_f32_e32 v140, v140
	v_rcp_f32_e32 v141, v141
	v_rcp_f32_e32 v142, v142
	v_rcp_f32_e32 v143, v143
	v_pk_mul_f32 v[118:119], v[118:119], v[130:131]
	v_pk_mul_f32 v[112:113], v[112:113], v[140:141]
	s_and_b64 vcc, exec, s[6:7]
	v_pk_mul_f32 v[114:115], v[114:115], v[142:143]
	s_cbranch_vccnz .LBB0_421
	v_lshlrev_b32_e32 v130, 16, v176
	v_and_b32_e32 v131, 0xffff0000, v176
	v_pk_add_f32 v[116:117], v[116:117], v[130:131]
	v_lshlrev_b32_e32 v130, 16, v177
	v_and_b32_e32 v131, 0xffff0000, v177
	v_pk_add_f32 v[118:119], v[118:119], v[130:131]
	v_lshlrev_b32_e32 v130, 16, v178
	v_and_b32_e32 v131, 0xffff0000, v178
	v_pk_add_f32 v[112:113], v[112:113], v[130:131]
	v_lshlrev_b32_e32 v130, 16, v179
	v_and_b32_e32 v131, 0xffff0000, v179
	v_pk_add_f32 v[114:115], v[114:115], v[130:131]
.LBB0_421:
	v_cvt_pk_bf16_f32 v116, v116, v117
	v_cvt_pk_bf16_f32 v117, v118, v119
	v_cvt_pk_bf16_f32 v118, v112, v113
	s_waitcnt vmcnt(6)
	v_lshlrev_b32_e32 v112, 16, v172
	v_and_b32_e32 v113, 0xffff0000, v172
	v_mul_f32_e32 v112, 0xbfb8aa3b, v112
	v_mul_f32_e32 v113, 0xbfb8aa3b, v113
	v_exp_f32_e32 v112, v112
	v_exp_f32_e32 v113, v113
	v_cvt_pk_bf16_f32 v119, v114, v115
	v_lshlrev_b32_e32 v114, 16, v173
	v_and_b32_e32 v115, 0xffff0000, v173
	v_add_f32_e32 v112, 1.0, v112
	v_add_f32_e32 v113, 1.0, v113
	v_mul_f32_e32 v114, 0xbfb8aa3b, v114
	v_mul_f32_e32 v115, 0xbfb8aa3b, v115
	v_rcp_f32_e32 v112, v112
	v_rcp_f32_e32 v113, v113
	v_exp_f32_e32 v114, v114
	v_exp_f32_e32 v115, v115
	global_store_dwordx4 v[128:129], v[116:119], off offset:256
	v_pk_mul_f32 v[108:109], v[108:109], v[112:113]
	v_add_f32_e32 v112, 1.0, v114
	v_add_f32_e32 v113, 1.0, v115
	v_lshlrev_b32_e32 v114, 16, v174
	v_and_b32_e32 v115, 0xffff0000, v174
	v_lshlrev_b32_e32 v116, 16, v175
	v_and_b32_e32 v117, 0xffff0000, v175
	v_mul_f32_e32 v114, 0xbfb8aa3b, v114
	v_mul_f32_e32 v115, 0xbfb8aa3b, v115
	v_mul_f32_e32 v116, 0xbfb8aa3b, v116
	v_mul_f32_e32 v117, 0xbfb8aa3b, v117
	v_exp_f32_e32 v114, v114
	v_exp_f32_e32 v115, v115
	v_exp_f32_e32 v116, v116
	v_exp_f32_e32 v117, v117
	v_add_f32_e32 v114, 1.0, v114
	v_add_f32_e32 v115, 1.0, v115
	v_add_f32_e32 v116, 1.0, v116
	v_add_f32_e32 v117, 1.0, v117
	v_rcp_f32_e32 v112, v112
	v_rcp_f32_e32 v113, v113
	v_rcp_f32_e32 v114, v114
	v_rcp_f32_e32 v115, v115
	v_rcp_f32_e32 v116, v116
	v_rcp_f32_e32 v117, v117
	v_pk_mul_f32 v[110:111], v[110:111], v[112:113]
	v_pk_mul_f32 v[112:113], v[104:105], v[114:115]
	s_and_b64 vcc, exec, s[6:7]
	v_pk_mul_f32 v[106:107], v[106:107], v[116:117]
	s_cbranch_vccnz .LBB0_423
	v_lshlrev_b32_e32 v104, 16, v168
	v_and_b32_e32 v105, 0xffff0000, v168
	v_pk_add_f32 v[108:109], v[108:109], v[104:105]
	v_lshlrev_b32_e32 v104, 16, v169
	v_and_b32_e32 v105, 0xffff0000, v169
	v_pk_add_f32 v[110:111], v[110:111], v[104:105]
	v_lshlrev_b32_e32 v104, 16, v170
	v_and_b32_e32 v105, 0xffff0000, v170
	v_pk_add_f32 v[112:113], v[112:113], v[104:105]
	v_lshlrev_b32_e32 v104, 16, v171
	v_and_b32_e32 v105, 0xffff0000, v171
	v_pk_add_f32 v[106:107], v[106:107], v[104:105]
; __device__ __forceinline__ unsigned cvt_pk_bf16(float lo, float hi) { unsigned r; asm volatile("v_cvt_pk_bf16_f32 %0, %1, %2" : "=v"(r) : "v"(lo), "v"(hi)); return r; }
; __device__ __forceinline__ float bf_lo(unsigned w) { return __uint_as_float(w << 16); }
; __device__ __forceinline__ float bf_hi(unsigned w) { return __uint_as_float(w & 0xffff0000u); }
; __device__ __forceinline__ float sigmoidf_(float x) { return __builtin_amdgcn_rcpf(1.0f + __builtin_amdgcn_exp2f(-x * 1.4426950408889634f)); }
;     __device__ __forceinline__ void operator()(const f32x4 (&acc)[2][2][4][2], const Unit& u, int wr, int wc, int fr, int fq) const {
;     ...
;             for (int m = 0; m < 4; ++m) { const int row = row0 + ai * HALF + m * 16;
; #pragma unroll
;                 for (int bj = 0; bj < 2; ++bj) { const int col = col0 + bj * HALF;
;                     const u32x4 g = gv[m][bj];
;                     bf16_t* mp = MIX + (size_t)row * 1024 + col;
;                     f32x4 v0 = acc[ai][bj][m][0], v1 = acc[ai][bj][m][1];
;                     v0[0] *= sigmoidf_(bf_lo(g.x)); v0[1] *= sigmoidf_(bf_hi(g.x)); v0[2] *= sigmoidf_(bf_lo(g.y)); v0[3] *= sigmoidf_(bf_hi(g.y));
;                     v1[0] *= sigmoidf_(bf_lo(g.z)); v1[1] *= sigmoidf_(bf_hi(g.z)); v1[2] *= sigmoidf_(bf_lo(g.w)); v1[3] *= sigmoidf_(bf_hi(g.w));
;                     if (br > 0) { const u32x4 p = pv[m][bj];
;                         v0[0] += bf_lo(p.x); v0[1] += bf_hi(p.x); v0[2] += bf_lo(p.y); v0[3] += bf_hi(p.y); v1[0] += bf_lo(p.z); v1[1] += bf_hi(p.z); v1[2] += bf_lo(p.w); v1[3] += bf_hi(p.w); }
;                     u32x4 w; w.x = cvt_pk_bf16(v0[0], v0[1]); w.y = cvt_pk_bf16(v0[2], v0[3]); w.z = cvt_pk_bf16(v1[0], v1[1]); w.w = cvt_pk_bf16(v1[2], v1[3]);
;                     *(u32x4*)mp = w; } }
.LBB0_423:
	v_cvt_pk_bf16_f32 v108, v108, v109
	v_cvt_pk_bf16_f32 v109, v110, v111
	v_cvt_pk_bf16_f32 v110, v112, v113
	s_nop 0
	v_cvt_pk_bf16_f32 v111, v106, v107
	s_waitcnt vmcnt(6)
	v_lshlrev_b32_e32 v106, 16, v164
	v_and_b32_e32 v107, 0xffff0000, v164
	v_mul_f32_e32 v106, 0xbfb8aa3b, v106
	v_mul_f32_e32 v107, 0xbfb8aa3b, v107
	v_exp_f32_e32 v106, v106
	v_exp_f32_e32 v107, v107
	v_lshl_add_u64 v[104:105], v[212:213], 1, v[224:225]
	global_store_dwordx4 v[104:105], v[108:111], off
	v_add_f32_e32 v106, 1.0, v106
	v_add_f32_e32 v107, 1.0, v107
	v_lshlrev_b32_e32 v108, 16, v165
	v_and_b32_e32 v109, 0xffff0000, v165
	v_mul_f32_e32 v108, 0xbfb8aa3b, v108
	v_mul_f32_e32 v109, 0xbfb8aa3b, v109
	v_rcp_f32_e32 v106, v106
	v_rcp_f32_e32 v107, v107
	v_exp_f32_e32 v108, v108
	v_exp_f32_e32 v109, v109
	v_lshlrev_b32_e32 v110, 16, v167
	v_pk_mul_f32 v[100:101], v[100:101], v[106:107]
	v_add_f32_e32 v106, 1.0, v108
	v_add_f32_e32 v107, 1.0, v109
	v_lshlrev_b32_e32 v108, 16, v166
	v_and_b32_e32 v109, 0xffff0000, v166
	v_and_b32_e32 v111, 0xffff0000, v167
	v_mul_f32_e32 v108, 0xbfb8aa3b, v108
	v_mul_f32_e32 v109, 0xbfb8aa3b, v109
	v_mul_f32_e32 v110, 0xbfb8aa3b, v110
	v_mul_f32_e32 v111, 0xbfb8aa3b, v111
	v_exp_f32_e32 v108, v108
	v_exp_f32_e32 v109, v109
	v_exp_f32_e32 v110, v110
	v_exp_f32_e32 v111, v111
	v_add_f32_e32 v108, 1.0, v108
	v_add_f32_e32 v109, 1.0, v109
	v_add_f32_e32 v110, 1.0, v110
	v_add_f32_e32 v111, 1.0, v111
	v_rcp_f32_e32 v106, v106
	v_rcp_f32_e32 v107, v107
	v_rcp_f32_e32 v108, v108
	v_rcp_f32_e32 v109, v109
	v_rcp_f32_e32 v110, v110
	v_rcp_f32_e32 v111, v111
	v_pk_mul_f32 v[102:103], v[102:103], v[106:107]
	v_pk_mul_f32 v[96:97], v[96:97], v[108:109]
	s_and_b64 vcc, exec, s[6:7]
	v_pk_mul_f32 v[98:99], v[98:99], v[110:111]
	s_cbranch_vccnz .LBB0_425
	v_lshlrev_b32_e32 v106, 16, v160
	v_and_b32_e32 v107, 0xffff0000, v160
	v_pk_add_f32 v[100:101], v[100:101], v[106:107]
	v_lshlrev_b32_e32 v106, 16, v161
	v_and_b32_e32 v107, 0xffff0000, v161
	v_pk_add_f32 v[102:103], v[102:103], v[106:107]
	v_lshlrev_b32_e32 v106, 16, v162
	v_and_b32_e32 v107, 0xffff0000, v162
	v_pk_add_f32 v[96:97], v[96:97], v[106:107]
	v_lshlrev_b32_e32 v106, 16, v163
	v_and_b32_e32 v107, 0xffff0000, v163
	v_pk_add_f32 v[98:99], v[98:99], v[106:107]
.LBB0_425:
	v_cvt_pk_bf16_f32 v100, v100, v101
	v_cvt_pk_bf16_f32 v101, v102, v103
	v_cvt_pk_bf16_f32 v102, v96, v97
	s_waitcnt vmcnt(6)
	v_lshlrev_b32_e32 v96, 16, v156
	v_and_b32_e32 v97, 0xffff0000, v156
	v_mul_f32_e32 v96, 0xbfb8aa3b, v96
	v_mul_f32_e32 v97, 0xbfb8aa3b, v97
	v_exp_f32_e32 v96, v96
	v_exp_f32_e32 v97, v97
	v_cvt_pk_bf16_f32 v103, v98, v99
	v_lshlrev_b32_e32 v98, 16, v157
	v_and_b32_e32 v99, 0xffff0000, v157
	v_add_f32_e32 v96, 1.0, v96
	v_add_f32_e32 v97, 1.0, v97
	v_mul_f32_e32 v98, 0xbfb8aa3b, v98
	v_mul_f32_e32 v99, 0xbfb8aa3b, v99
	v_rcp_f32_e32 v96, v96
	v_rcp_f32_e32 v97, v97
	v_exp_f32_e32 v98, v98
	v_exp_f32_e32 v99, v99
	global_store_dwordx4 v[104:105], v[100:103], off offset:256
	v_pk_mul_f32 v[92:93], v[92:93], v[96:97]
	v_add_f32_e32 v96, 1.0, v98
	v_add_f32_e32 v97, 1.0, v99
	v_lshlrev_b32_e32 v98, 16, v158
	v_and_b32_e32 v99, 0xffff0000, v158
	v_lshlrev_b32_e32 v100, 16, v159
	v_and_b32_e32 v101, 0xffff0000, v159
	v_mul_f32_e32 v98, 0xbfb8aa3b, v98
	v_mul_f32_e32 v99, 0xbfb8aa3b, v99
	v_mul_f32_e32 v100, 0xbfb8aa3b, v100
	v_mul_f32_e32 v101, 0xbfb8aa3b, v101
	v_exp_f32_e32 v98, v98
	v_exp_f32_e32 v99, v99
	v_exp_f32_e32 v100, v100
	v_exp_f32_e32 v101, v101
	v_add_f32_e32 v98, 1.0, v98
	v_add_f32_e32 v99, 1.0, v99
	v_add_f32_e32 v100, 1.0, v100
	v_add_f32_e32 v101, 1.0, v101
	v_rcp_f32_e32 v96, v96
	v_rcp_f32_e32 v97, v97
	v_rcp_f32_e32 v98, v98
	v_rcp_f32_e32 v99, v99
	v_rcp_f32_e32 v100, v100
	v_rcp_f32_e32 v101, v101
	v_pk_mul_f32 v[94:95], v[94:95], v[96:97]
	v_pk_mul_f32 v[96:97], v[88:89], v[98:99]
	s_and_b64 vcc, exec, s[6:7]
	v_pk_mul_f32 v[90:91], v[90:91], v[100:101]
	s_cbranch_vccnz .LBB0_427
	v_lshlrev_b32_e32 v88, 16, v152
	v_and_b32_e32 v89, 0xffff0000, v152
	v_pk_add_f32 v[92:93], v[92:93], v[88:89]
	v_lshlrev_b32_e32 v88, 16, v153
	v_and_b32_e32 v89, 0xffff0000, v153
	v_pk_add_f32 v[94:95], v[94:95], v[88:89]
	v_lshlrev_b32_e32 v88, 16, v154
	v_and_b32_e32 v89, 0xffff0000, v154
	v_pk_add_f32 v[96:97], v[96:97], v[88:89]
	v_lshlrev_b32_e32 v88, 16, v155
	v_and_b32_e32 v89, 0xffff0000, v155
	v_pk_add_f32 v[90:91], v[90:91], v[88:89]
; __device__ __forceinline__ unsigned cvt_pk_bf16(float lo, float hi) { unsigned r; asm volatile("v_cvt_pk_bf16_f32 %0, %1, %2" : "=v"(r) : "v"(lo), "v"(hi)); return r; }
; __device__ __forceinline__ float bf_lo(unsigned w) { return __uint_as_float(w << 16); }
; __device__ __forceinline__ float bf_hi(unsigned w) { return __uint_as_float(w & 0xffff0000u); }
; __device__ __forceinline__ float sigmoidf_(float x) { return __builtin_amdgcn_rcpf(1.0f + __builtin_amdgcn_exp2f(-x * 1.4426950408889634f)); }
;     __device__ __forceinline__ void operator()(const f32x4 (&acc)[2][2][4][2], const Unit& u, int wr, int wc, int fr, int fq) const {
;     ...
;             for (int m = 0; m < 4; ++m) { const int row = row0 + ai * HALF + m * 16;
; #pragma unroll
;                 for (int bj = 0; bj < 2; ++bj) { const int col = col0 + bj * HALF;
;                     const u32x4 g = gv[m][bj];
;                     bf16_t* mp = MIX + (size_t)row * 1024 + col;
;                     f32x4 v0 = acc[ai][bj][m][0], v1 = acc[ai][bj][m][1];
;                     v0[0] *= sigmoidf_(bf_lo(g.x)); v0[1] *= sigmoidf_(bf_hi(g.x)); v0[2] *= sigmoidf_(bf_lo(g.y)); v0[3] *= sigmoidf_(bf_hi(g.y));
;                     v1[0] *= sigmoidf_(bf_lo(g.z)); v1[1] *= sigmoidf_(bf_hi(g.z)); v1[2] *= sigmoidf_(bf_lo(g.w)); v1[3] *= sigmoidf_(bf_hi(g.w));
;                     if (br > 0) { const u32x4 p = pv[m][bj];
;                         v0[0] += bf_lo(p.x); v0[1] += bf_hi(p.x); v0[2] += bf_lo(p.y); v0[3] += bf_hi(p.y); v1[0] += bf_lo(p.z); v1[1] += bf_hi(p.z); v1[2] += bf_lo(p.w); v1[3] += bf_hi(p.w); }
;                     u32x4 w; w.x = cvt_pk_bf16(v0[0], v0[1]); w.y = cvt_pk_bf16(v0[2], v0[3]); w.z = cvt_pk_bf16(v1[0], v1[1]); w.w = cvt_pk_bf16(v1[2], v1[3]);
;                     *(u32x4*)mp = w; } }
.LBB0_427:
	v_cvt_pk_bf16_f32 v92, v92, v93
	v_cvt_pk_bf16_f32 v93, v94, v95
	v_cvt_pk_bf16_f32 v94, v96, v97
	s_nop 0
	v_cvt_pk_bf16_f32 v95, v90, v91
	s_waitcnt vmcnt(6)
	v_lshlrev_b32_e32 v90, 16, v148
	v_and_b32_e32 v91, 0xffff0000, v148
	v_mul_f32_e32 v90, 0xbfb8aa3b, v90
	v_mul_f32_e32 v91, 0xbfb8aa3b, v91
	v_exp_f32_e32 v90, v90
	v_exp_f32_e32 v91, v91
	v_lshl_add_u64 v[88:89], v[212:213], 1, v[222:223]
	global_store_dwordx4 v[88:89], v[92:95], off
	v_add_f32_e32 v90, 1.0, v90
	v_add_f32_e32 v91, 1.0, v91
	v_lshlrev_b32_e32 v92, 16, v149
	v_and_b32_e32 v93, 0xffff0000, v149
	v_mul_f32_e32 v92, 0xbfb8aa3b, v92
	v_mul_f32_e32 v93, 0xbfb8aa3b, v93
	v_rcp_f32_e32 v90, v90
	v_rcp_f32_e32 v91, v91
	v_exp_f32_e32 v92, v92
	v_exp_f32_e32 v93, v93
	v_lshlrev_b32_e32 v94, 16, v151
	v_pk_mul_f32 v[84:85], v[84:85], v[90:91]
	v_add_f32_e32 v90, 1.0, v92
	v_add_f32_e32 v91, 1.0, v93
	v_lshlrev_b32_e32 v92, 16, v150
	v_and_b32_e32 v93, 0xffff0000, v150
	v_and_b32_e32 v95, 0xffff0000, v151
	v_mul_f32_e32 v92, 0xbfb8aa3b, v92
	v_mul_f32_e32 v93, 0xbfb8aa3b, v93
	v_mul_f32_e32 v94, 0xbfb8aa3b, v94
	v_mul_f32_e32 v95, 0xbfb8aa3b, v95
	v_exp_f32_e32 v92, v92
	v_exp_f32_e32 v93, v93
	v_exp_f32_e32 v94, v94
	v_exp_f32_e32 v95, v95
	v_add_f32_e32 v92, 1.0, v92
	v_add_f32_e32 v93, 1.0, v93
	v_add_f32_e32 v94, 1.0, v94
	v_add_f32_e32 v95, 1.0, v95
	v_rcp_f32_e32 v90, v90
	v_rcp_f32_e32 v91, v91
	v_rcp_f32_e32 v92, v92
	v_rcp_f32_e32 v93, v93
	v_rcp_f32_e32 v94, v94
	v_rcp_f32_e32 v95, v95
	v_pk_mul_f32 v[86:87], v[86:87], v[90:91]
	v_pk_mul_f32 v[80:81], v[80:81], v[92:93]
	s_and_b64 vcc, exec, s[6:7]
	v_pk_mul_f32 v[82:83], v[82:83], v[94:95]
	s_cbranch_vccnz .LBB0_429
	v_lshlrev_b32_e32 v90, 16, v144
	v_and_b32_e32 v91, 0xffff0000, v144
	v_pk_add_f32 v[84:85], v[84:85], v[90:91]
	v_lshlrev_b32_e32 v90, 16, v145
	v_and_b32_e32 v91, 0xffff0000, v145
	v_pk_add_f32 v[86:87], v[86:87], v[90:91]
	v_lshlrev_b32_e32 v90, 16, v146
	v_and_b32_e32 v91, 0xffff0000, v146
	v_pk_add_f32 v[80:81], v[80:81], v[90:91]
	v_lshlrev_b32_e32 v90, 16, v147
	v_and_b32_e32 v91, 0xffff0000, v147
	v_pk_add_f32 v[82:83], v[82:83], v[90:91]
.LBB0_429:
	v_cvt_pk_bf16_f32 v84, v84, v85
	v_cvt_pk_bf16_f32 v85, v86, v87
	v_cvt_pk_bf16_f32 v86, v80, v81
	s_waitcnt vmcnt(6)
	v_lshlrev_b32_e32 v80, 16, v136
	v_and_b32_e32 v81, 0xffff0000, v136
	v_mul_f32_e32 v80, 0xbfb8aa3b, v80
	v_mul_f32_e32 v81, 0xbfb8aa3b, v81
	v_exp_f32_e32 v80, v80
	v_exp_f32_e32 v81, v81
	v_cvt_pk_bf16_f32 v87, v82, v83
	v_lshlrev_b32_e32 v82, 16, v137
	v_and_b32_e32 v83, 0xffff0000, v137
	v_add_f32_e32 v80, 1.0, v80
	v_add_f32_e32 v81, 1.0, v81
	v_mul_f32_e32 v82, 0xbfb8aa3b, v82
	v_mul_f32_e32 v83, 0xbfb8aa3b, v83
	v_rcp_f32_e32 v80, v80
	v_rcp_f32_e32 v81, v81
	v_exp_f32_e32 v82, v82
	v_exp_f32_e32 v83, v83
	global_store_dwordx4 v[88:89], v[84:87], off offset:256
	v_pk_mul_f32 v[76:77], v[76:77], v[80:81]
	v_add_f32_e32 v80, 1.0, v82
	v_add_f32_e32 v81, 1.0, v83
	v_lshlrev_b32_e32 v82, 16, v138
	v_and_b32_e32 v83, 0xffff0000, v138
	v_lshlrev_b32_e32 v84, 16, v139
	v_and_b32_e32 v85, 0xffff0000, v139
	v_mul_f32_e32 v82, 0xbfb8aa3b, v82
	v_mul_f32_e32 v83, 0xbfb8aa3b, v83
	v_mul_f32_e32 v84, 0xbfb8aa3b, v84
	v_mul_f32_e32 v85, 0xbfb8aa3b, v85
	v_exp_f32_e32 v82, v82
	v_exp_f32_e32 v83, v83
	v_exp_f32_e32 v84, v84
	v_exp_f32_e32 v85, v85
	v_add_f32_e32 v82, 1.0, v82
	v_add_f32_e32 v83, 1.0, v83
	v_add_f32_e32 v84, 1.0, v84
	v_add_f32_e32 v85, 1.0, v85
	v_rcp_f32_e32 v80, v80
	v_rcp_f32_e32 v81, v81
	v_rcp_f32_e32 v82, v82
	v_rcp_f32_e32 v83, v83
	v_rcp_f32_e32 v84, v84
	v_rcp_f32_e32 v85, v85
	v_pk_mul_f32 v[78:79], v[78:79], v[80:81]
	v_pk_mul_f32 v[80:81], v[72:73], v[82:83]
	s_and_b64 vcc, exec, s[6:7]
	v_pk_mul_f32 v[74:75], v[74:75], v[84:85]
	s_cbranch_vccnz .LBB0_431
	v_lshlrev_b32_e32 v72, 16, v132
	v_and_b32_e32 v73, 0xffff0000, v132
	v_pk_add_f32 v[76:77], v[76:77], v[72:73]
	v_lshlrev_b32_e32 v72, 16, v133
	v_and_b32_e32 v73, 0xffff0000, v133
	v_pk_add_f32 v[78:79], v[78:79], v[72:73]
	v_lshlrev_b32_e32 v72, 16, v134
	v_and_b32_e32 v73, 0xffff0000, v134
	v_pk_add_f32 v[80:81], v[80:81], v[72:73]
	v_lshlrev_b32_e32 v72, 16, v135
	v_and_b32_e32 v73, 0xffff0000, v135
	v_pk_add_f32 v[74:75], v[74:75], v[72:73]
.LBB0_431:
	v_cvt_pk_bf16_f32 v76, v76, v77
	v_cvt_pk_bf16_f32 v77, v78, v79
	v_cvt_pk_bf16_f32 v78, v80, v81
	s_nop 0
	v_cvt_pk_bf16_f32 v79, v74, v75
	s_waitcnt vmcnt(6)
	v_lshlrev_b32_e32 v74, 16, v124
	v_and_b32_e32 v75, 0xffff0000, v124
	v_mul_f32_e32 v74, 0xbfb8aa3b, v74
	v_mul_f32_e32 v75, 0xbfb8aa3b, v75
	v_exp_f32_e32 v74, v74
	v_exp_f32_e32 v75, v75
	v_lshl_add_u64 v[72:73], v[212:213], 1, v[220:221]
	global_store_dwordx4 v[72:73], v[76:79], off
	v_add_f32_e32 v74, 1.0, v74
	v_add_f32_e32 v75, 1.0, v75
	v_lshlrev_b32_e32 v76, 16, v125
	v_and_b32_e32 v77, 0xffff0000, v125
	v_mul_f32_e32 v76, 0xbfb8aa3b, v76
	v_mul_f32_e32 v77, 0xbfb8aa3b, v77
	v_rcp_f32_e32 v74, v74
	v_rcp_f32_e32 v75, v75
	v_exp_f32_e32 v76, v76
	v_exp_f32_e32 v77, v77
	v_lshlrev_b32_e32 v78, 16, v127
	v_pk_mul_f32 v[68:69], v[68:69], v[74:75]
	v_add_f32_e32 v74, 1.0, v76
	v_add_f32_e32 v75, 1.0, v77
	v_lshlrev_b32_e32 v76, 16, v126
	v_and_b32_e32 v77, 0xffff0000, v126
	v_and_b32_e32 v79, 0xffff0000, v127
	v_mul_f32_e32 v76, 0xbfb8aa3b, v76
	v_mul_f32_e32 v77, 0xbfb8aa3b, v77
	v_mul_f32_e32 v78, 0xbfb8aa3b, v78
	v_mul_f32_e32 v79, 0xbfb8aa3b, v79
	v_exp_f32_e32 v76, v76
	v_exp_f32_e32 v77, v77
	v_exp_f32_e32 v78, v78
	v_exp_f32_e32 v79, v79
	v_add_f32_e32 v76, 1.0, v76
	v_add_f32_e32 v77, 1.0, v77
	v_add_f32_e32 v78, 1.0, v78
	v_add_f32_e32 v79, 1.0, v79
	v_rcp_f32_e32 v74, v74
	v_rcp_f32_e32 v75, v75
	v_rcp_f32_e32 v76, v76
	v_rcp_f32_e32 v77, v77
	v_rcp_f32_e32 v78, v78
	v_rcp_f32_e32 v79, v79
	v_pk_mul_f32 v[70:71], v[70:71], v[74:75]
	v_pk_mul_f32 v[64:65], v[64:65], v[76:77]
	s_and_b64 vcc, exec, s[6:7]
	v_pk_mul_f32 v[66:67], v[66:67], v[78:79]
	s_cbranch_vccnz .LBB0_433
	v_lshlrev_b32_e32 v74, 16, v120
	v_and_b32_e32 v75, 0xffff0000, v120
	v_pk_add_f32 v[68:69], v[68:69], v[74:75]
	v_lshlrev_b32_e32 v74, 16, v121
	v_and_b32_e32 v75, 0xffff0000, v121
	v_pk_add_f32 v[70:71], v[70:71], v[74:75]
	v_lshlrev_b32_e32 v74, 16, v122
	v_and_b32_e32 v75, 0xffff0000, v122
	v_pk_add_f32 v[64:65], v[64:65], v[74:75]
	v_lshlrev_b32_e32 v74, 16, v123
	v_and_b32_e32 v75, 0xffff0000, v123
	v_pk_add_f32 v[66:67], v[66:67], v[74:75]
